# split-K tail of the layer-0 MLP2 GEMM cut into 8 K-parts instead of 16 (half the atomic traffic)
# speedup vs baseline: 1.0408x; 1.0016x over previous
.LBB0_839:
	s_or_b64 exec, exec, s[0:1]
	v_cvt_f32_u32_e32 v0, s51
	s_sub_i32 s2, 0, s51
	s_abs_i32 s1, s33
	s_ashr_i32 s0, s33, 31
	s_waitcnt lgkmcnt(0)
	v_rcp_iflag_f32_e32 v1, v0
	v_mov_b32_e32 v0, v170
	s_mov_b32 s26, 1
	v_mul_f32_e32 v1, 0x4f7ffffe, v1
	v_cvt_u32_f32_e32 v1, v1
	s_barrier
	v_readfirstlane_b32 s3, v1
	s_mul_i32 s2, s2, s3
	s_mul_hi_u32 s2, s3, s2
	s_add_i32 s3, s3, s2
	s_mul_hi_u32 s2, s1, s3
	s_mul_i32 s2, s2, s51
	s_sub_i32 s1, s1, s2
	s_sub_i32 s2, s1, s51
	s_cmp_ge_u32 s1, s51
	s_cselect_b32 s1, s2, s1
	s_sub_i32 s2, s1, s51
	s_cmp_ge_u32 s1, s51
	s_cselect_b32 s1, s2, s1
	s_xor_b32 s1, s1, s0
	s_sub_i32 s0, s1, s0
	s_cmp_lt_i32 s0, 1
	s_cbranch_scc1 .LBB0_842
	v_cvt_f32_u32_e32 v1, s0
	s_sub_i32 s2, 0, s0
	s_mov_b32 s1, 1
	v_rcp_iflag_f32_e32 v1, v1
	s_nop 0
	v_mul_f32_e32 v1, 0x4f7ffffe, v1
	v_cvt_u32_f32_e32 v1, v1
	s_nop 0
	v_readfirstlane_b32 s3, v1
	s_mul_i32 s2, s2, s3
	s_mul_hi_u32 s2, s3, s2
	s_add_i32 s3, s3, s2
	s_mul_hi_u32 s2, s51, s3
	s_mul_i32 s3, s2, s0
	s_sub_i32 s3, s51, s3
	s_add_i32 s4, s2, 1
	s_sub_i32 s5, s3, s0
	s_cmp_ge_u32 s3, s0
	s_cselect_b32 s2, s4, s2
	s_cselect_b32 s3, s5, s3
	s_add_i32 s4, s2, 1
	s_cmp_ge_u32 s3, s0
	s_cselect_b32 s2, s4, s2
	s_min_u32 s2, s2, 8
